# conv tile tap loop: next chunk's 8 weight loads stay in flight under the current chunk's FMAs (masks applied behind the chunk's final wait)
# speedup vs baseline: 1.0015x; 1.0015x over previous
; #define LAS __attribute__((address_space(3)))
; __device__ __forceinline__ void conv_tile_v1(Frame& F, const Args& AR, int l, int tile) {
;     ...
;     {
;         const float* wp = AR.in[I_CONVW] + (size_t)l * 31 * 512 + c;
;         float wc[8];
; #pragma unroll
;         for (int t = 0; t < 8; ++t) wc[t] = wp[t * 512];
; #pragma unroll 1
;         for (int kb = 0; kb < 4; ++kb) {
;             float wn[8];
; #pragma unroll
;             for (int t = 0; t < 8; ++t) { const int k = 8 * (kb + 1) + t; wn[t] = wp[(k < 31 ? k : 30) * 512]; if (k >= 31) wn[t] = 0.f; }
;             const LAS float* hb = hh + (8 * kb) * 512 + c;
;             float hv[23];
; #pragma unroll
;             for (int j = 0; j < 23; ++j) hv[j] = hb[j * 512];
; #pragma unroll
;             for (int t = 0; t < 8; ++t)
; #pragma unroll
;                 for (int i = 0; i < 16; ++i) ov[i] += hv[i + t] * wc[t];
.LBB0_1365:
	s_min_u32 s4, s0, 22
	s_lshl_b32 s16, s4, 11
	v_lshl_add_u64 v[40:41], v[20:21], 0, s[16:17]
	v_add_co_u32_e32 v40, vcc, s7, v40
	s_cmp_gt_u32 s1, 2
	s_nop 0
	v_addc_co_u32_e32 v41, vcc, 0, v41, vcc
	global_load_dword v27, v[40:41], off
	s_cselect_b64 s[4:5], -1, 0
	s_min_u32 s6, s0, 21
	s_lshl_b32 s16, s6, 11
	v_lshl_add_u64 v[40:41], v[20:21], 0, s[16:17]
	v_add_co_u32_e32 v40, vcc, s7, v40
	s_min_u32 s6, s0, 20
	s_nop 0
	v_addc_co_u32_e32 v41, vcc, 0, v41, vcc
	s_lshl_b32 s16, s6, 11
	s_min_u32 s6, s0, 19
	global_load_dword v25, v[40:41], off offset:2048
	v_lshl_add_u64 v[40:41], v[20:21], 0, s[16:17]
	v_add_co_u32_e32 v40, vcc, s9, v40
	s_lshl_b32 s16, s6, 11
	s_nop 0
	v_addc_co_u32_e32 v41, vcc, 0, v41, vcc
	global_load_dword v29, v[40:41], off
	v_lshl_add_u64 v[40:41], v[20:21], 0, s[16:17]
	v_add_co_u32_e32 v40, vcc, s9, v40
	s_min_u32 s6, s0, 18
	s_nop 0
	v_addc_co_u32_e32 v41, vcc, 0, v41, vcc
	s_lshl_b32 s16, s6, 11
	global_load_dword v31, v[40:41], off offset:2048
	v_lshl_add_u64 v[40:41], v[20:21], 0, s[16:17]
	v_add_co_u32_e32 v40, vcc, s8, v40
	s_min_u32 s6, s0, 17
	s_nop 0
	v_addc_co_u32_e32 v41, vcc, 0, v41, vcc
	s_lshl_b32 s16, s6, 11
	global_load_dword v33, v[40:41], off
	v_lshl_add_u64 v[40:41], v[20:21], 0, s[16:17]
	v_add_co_u32_e32 v40, vcc, s8, v40
	s_min_u32 s6, s0, 16
	s_nop 0
	v_addc_co_u32_e32 v41, vcc, 0, v41, vcc
	s_lshl_b32 s16, s6, 11
	global_load_dword v35, v[40:41], off offset:2048
	v_lshl_add_u64 v[40:41], v[20:21], 0, s[16:17]
	v_add_co_u32_e32 v40, vcc, s15, v40
	s_nop 1
	v_addc_co_u32_e32 v41, vcc, 0, v41, vcc
	global_load_dword v37, v[40:41], off
	s_min_u32 s4, s0, 15
	s_lshl_b32 s16, s4, 11
	v_lshl_add_u64 v[40:41], v[20:21], 0, s[16:17]
	v_add_co_u32_e32 v40, vcc, s15, v40
	s_cmp_lt_u32 s1, 2
	s_nop 0
	v_addc_co_u32_e32 v41, vcc, 0, v41, vcc
	global_load_dword v38, v[40:41], off offset:2048
	s_waitcnt vmcnt(8)
	ds_read2st64_b32 v[42:43], v39 offset1:8
	ds_read2st64_b32 v[44:45], v39 offset0:16 offset1:24
	ds_read2st64_b32 v[46:47], v39 offset0:32 offset1:40
	ds_read2st64_b32 v[48:49], v39 offset0:48 offset1:56
	ds_read2st64_b32 v[50:51], v39 offset0:64 offset1:72
	ds_read2st64_b32 v[52:53], v39 offset0:80 offset1:88
	ds_read2st64_b32 v[54:55], v39 offset0:96 offset1:104
	ds_read2st64_b32 v[56:57], v39 offset0:112 offset1:120
	ds_read2st64_b32 v[58:59], v39 offset0:128 offset1:136
	ds_read2st64_b32 v[60:61], v39 offset0:144 offset1:152
	ds_read2st64_b32 v[62:63], v39 offset0:160 offset1:168
	ds_read_b32 v65, v39 offset:45056
	s_waitcnt lgkmcnt(11)
	v_pk_fma_f32 v[18:19], v[22:23], v[42:43], v[18:19] op_sel_hi:[0,1,1]
	v_mov_b32_e32 v42, v43
	s_waitcnt lgkmcnt(10)
	v_mov_b32_e32 v43, v44
	v_pk_fma_f32 v[18:19], v[24:25], v[42:43], v[18:19] op_sel_hi:[0,1,1]
	v_mov_b32_e32 v42, v45
	s_waitcnt lgkmcnt(9)
	v_mov_b32_e32 v43, v46
	v_pk_fma_f32 v[4:5], v[22:23], v[44:45], v[4:5] op_sel_hi:[0,1,1]
	v_pk_fma_f32 v[4:5], v[24:25], v[42:43], v[4:5] op_sel_hi:[0,1,1]
	v_mov_b32_e32 v66, v47
	s_waitcnt lgkmcnt(8)
	v_mov_b32_e32 v67, v48
	v_pk_fma_f32 v[4:5], v[26:27], v[46:47], v[4:5] op_sel_hi:[0,1,1]
	v_pk_fma_f32 v[2:3], v[22:23], v[46:47], v[2:3] op_sel_hi:[0,1,1]
	v_pk_fma_f32 v[4:5], v[28:29], v[66:67], v[4:5] op_sel_hi:[0,1,1]
	v_pk_fma_f32 v[2:3], v[24:25], v[66:67], v[2:3] op_sel_hi:[0,1,1]
	v_mov_b32_e32 v68, v49
	s_waitcnt lgkmcnt(7)
	v_mov_b32_e32 v69, v50
	v_pk_fma_f32 v[4:5], v[30:31], v[48:49], v[4:5] op_sel_hi:[0,1,1]
	v_pk_fma_f32 v[2:3], v[26:27], v[48:49], v[2:3] op_sel_hi:[0,1,1]
	v_pk_fma_f32 v[14:15], v[22:23], v[48:49], v[14:15] op_sel_hi:[0,1,1]
	v_pk_fma_f32 v[18:19], v[26:27], v[44:45], v[18:19] op_sel_hi:[0,1,1]
	v_pk_fma_f32 v[4:5], v[32:33], v[68:69], v[4:5] op_sel_hi:[0,1,1]
	v_pk_fma_f32 v[2:3], v[28:29], v[68:69], v[2:3] op_sel_hi:[0,1,1]
	v_pk_fma_f32 v[14:15], v[24:25], v[68:69], v[14:15] op_sel_hi:[0,1,1]
	v_pk_fma_f32 v[18:19], v[28:29], v[42:43], v[18:19] op_sel_hi:[0,1,1]
	v_pk_fma_f32 v[4:5], v[34:35], v[50:51], v[4:5] op_sel_hi:[0,1,1]
	v_mov_b32_e32 v42, v51
	s_waitcnt lgkmcnt(6)
	v_mov_b32_e32 v43, v52
	v_pk_fma_f32 v[2:3], v[30:31], v[50:51], v[2:3] op_sel_hi:[0,1,1]
	v_pk_fma_f32 v[14:15], v[26:27], v[50:51], v[14:15] op_sel_hi:[0,1,1]
	v_pk_fma_f32 v[12:13], v[22:23], v[50:51], v[12:13] op_sel_hi:[0,1,1]
	v_pk_fma_f32 v[18:19], v[30:31], v[46:47], v[18:19] op_sel_hi:[0,1,1]
	v_pk_fma_f32 v[4:5], v[36:37], v[42:43], v[4:5] op_sel_hi:[0,1,1]
	v_pk_fma_f32 v[2:3], v[32:33], v[42:43], v[2:3] op_sel_hi:[0,1,1]
	v_mov_b32_e32 v44, v53
	s_waitcnt lgkmcnt(5)
	v_mov_b32_e32 v45, v54
	v_pk_fma_f32 v[14:15], v[28:29], v[42:43], v[14:15] op_sel_hi:[0,1,1]
	v_mov_b32_e32 v46, v55
	s_waitcnt lgkmcnt(4)
	v_mov_b32_e32 v47, v56
	v_pk_fma_f32 v[12:13], v[24:25], v[42:43], v[12:13] op_sel_hi:[0,1,1]
	v_mov_b32_e32 v42, v57
	s_waitcnt lgkmcnt(3)
	v_mov_b32_e32 v43, v58
	v_pk_fma_f32 v[10:11], v[22:23], v[52:53], v[10:11] op_sel_hi:[0,1,1]
	v_pk_fma_f32 v[8:9], v[22:23], v[54:55], v[8:9] op_sel_hi:[0,1,1]
	v_pk_fma_f32 v[6:7], v[22:23], v[56:57], v[6:7] op_sel_hi:[0,1,1]
	v_pk_fma_f32 v[2:3], v[34:35], v[52:53], v[2:3] op_sel_hi:[0,1,1]
	v_pk_fma_f32 v[14:15], v[30:31], v[52:53], v[14:15] op_sel_hi:[0,1,1]
	v_pk_fma_f32 v[12:13], v[26:27], v[52:53], v[12:13] op_sel_hi:[0,1,1]
	v_pk_fma_f32 v[10:11], v[24:25], v[44:45], v[10:11] op_sel_hi:[0,1,1]
	v_pk_fma_f32 v[8:9], v[24:25], v[46:47], v[8:9] op_sel_hi:[0,1,1]
	v_pk_fma_f32 v[6:7], v[24:25], v[42:43], v[6:7] op_sel_hi:[0,1,1]
	v_pk_fma_f32 v[2:3], v[36:37], v[44:45], v[2:3] op_sel_hi:[0,1,1]
	v_pk_fma_f32 v[14:15], v[32:33], v[44:45], v[14:15] op_sel_hi:[0,1,1]
	v_pk_fma_f32 v[12:13], v[28:29], v[44:45], v[12:13] op_sel_hi:[0,1,1]
	v_pk_fma_f32 v[10:11], v[26:27], v[54:55], v[10:11] op_sel_hi:[0,1,1]
	v_mov_b32_e32 v44, v59
	s_waitcnt lgkmcnt(2)
; __device__ __forceinline__ void conv_tile_v1(Frame& F, const Args& AR, int l, int tile) {
;     ...
; #pragma unroll
;             for (int t = 0; t < 8; ++t)
; #pragma unroll
;                 for (int i = 0; i < 16; ++i) ov[i] += hv[i + t] * wc[t];
; #pragma unroll
;             for (int t = 0; t < 8; ++t) wc[t] = wn[t];
;         }
;     }
;     __syncthreads();
; #pragma unroll
;     for (int i = 0; i < 16; ++i) hh[i * 512 + c] = ov[i];
	v_mov_b32_e32 v45, v60
	v_pk_fma_f32 v[8:9], v[26:27], v[56:57], v[8:9] op_sel_hi:[0,1,1]
	v_pk_fma_f32 v[6:7], v[26:27], v[58:59], v[6:7] op_sel_hi:[0,1,1]
	v_pk_fma_f32 v[14:15], v[34:35], v[54:55], v[14:15] op_sel_hi:[0,1,1]
	v_pk_fma_f32 v[12:13], v[30:31], v[54:55], v[12:13] op_sel_hi:[0,1,1]
	v_pk_fma_f32 v[10:11], v[28:29], v[46:47], v[10:11] op_sel_hi:[0,1,1]
	v_pk_fma_f32 v[8:9], v[28:29], v[42:43], v[8:9] op_sel_hi:[0,1,1]
	v_pk_fma_f32 v[6:7], v[28:29], v[44:45], v[6:7] op_sel_hi:[0,1,1]
	v_pk_fma_f32 v[14:15], v[36:37], v[46:47], v[14:15] op_sel_hi:[0,1,1]
	v_pk_fma_f32 v[12:13], v[32:33], v[46:47], v[12:13] op_sel_hi:[0,1,1]
	v_pk_fma_f32 v[10:11], v[30:31], v[56:57], v[10:11] op_sel_hi:[0,1,1]
	v_pk_fma_f32 v[8:9], v[30:31], v[58:59], v[8:9] op_sel_hi:[0,1,1]
	v_mov_b32_e32 v46, v61
	s_waitcnt lgkmcnt(1)
	v_mov_b32_e32 v47, v62
	v_pk_fma_f32 v[6:7], v[30:31], v[60:61], v[6:7] op_sel_hi:[0,1,1]
	s_cselect_b64 vcc, -1, 0
	v_pk_fma_f32 v[18:19], v[32:33], v[66:67], v[18:19] op_sel_hi:[0,1,1]
	v_pk_fma_f32 v[10:11], v[32:33], v[42:43], v[10:11] op_sel_hi:[0,1,1]
	v_pk_fma_f32 v[8:9], v[32:33], v[44:45], v[8:9] op_sel_hi:[0,1,1]
	v_pk_fma_f32 v[6:7], v[32:33], v[46:47], v[6:7] op_sel_hi:[0,1,1]
	v_add_u32_e32 v40, 0x4000, v39
	v_pk_fma_f32 v[18:19], v[34:35], v[48:49], v[18:19] op_sel_hi:[0,1,1]
	s_waitcnt vmcnt(0)
	v_cndmask_b32_e32 v38, 0, v38, vcc
	s_cmp_gt_u32 s1, 2
	s_cselect_b64 vcc, -1, 0
	s_nop 1
	v_cndmask_b32_e64 v27, v27, 0, vcc
	v_cndmask_b32_e64 v25, v25, 0, vcc
	v_cndmask_b32_e64 v29, v29, 0, vcc
	v_cndmask_b32_e64 v31, v31, 0, vcc
	v_cndmask_b32_e64 v33, v33, 0, vcc
	v_cndmask_b32_e64 v35, v35, 0, vcc
	v_cndmask_b32_e64 v37, v37, 0, vcc
	v_pk_fma_f32 v[12:13], v[34:35], v[56:57], v[12:13] op_sel_hi:[0,1,1]
	v_pk_fma_f32 v[10:11], v[34:35], v[58:59], v[10:11] op_sel_hi:[0,1,1]
	v_pk_fma_f32 v[8:9], v[34:35], v[60:61], v[8:9] op_sel_hi:[0,1,1]
	v_pk_fma_f32 v[6:7], v[34:35], v[62:63], v[6:7] op_sel_hi:[0,1,1]
	v_mov_b32_e32 v64, v63
	s_add_i32 s1, s1, 1
	s_add_i32 s0, s0, 8
	v_pk_fma_f32 v[18:19], v[36:37], v[68:69], v[18:19] op_sel_hi:[0,1,1]
	v_pk_fma_f32 v[12:13], v[36:37], v[42:43], v[12:13] op_sel_hi:[0,1,1]
	v_pk_fma_f32 v[10:11], v[36:37], v[44:45], v[10:11] op_sel_hi:[0,1,1]
	v_pk_fma_f32 v[8:9], v[36:37], v[46:47], v[8:9] op_sel_hi:[0,1,1]
	s_waitcnt lgkmcnt(0)
	v_pk_fma_f32 v[6:7], v[36:37], v[64:65], v[6:7] op_sel_hi:[0,1,1]
	s_cmp_eq_u32 s1, 4
	v_mov_b32_e32 v39, v40
	v_mov_b32_e32 v22, v27
	v_mov_b32_e32 v24, v25
	v_mov_b32_e32 v26, v29
	v_mov_b32_e32 v28, v31
	v_mov_b32_e32 v30, v33
	v_mov_b32_e32 v32, v35
	v_mov_b32_e32 v34, v37
	v_mov_b32_e32 v36, v38
	s_cbranch_scc0 .LBB0_1365
	s_lshl_b32 s0, s12, 12
	s_add_i32 s0, s0, 0
	v_cmp_lt_i32_e32 vcc, v219, v218
	v_lshl_add_u32 v31, v149, 2, s0
	s_nop 0
	v_cndmask_b32_e32 v20, v217, v219, vcc
	v_lshlrev_b32_e32 v40, 2, v20
	s_barrier
	ds_write2st64_b32 v23, v18, v19 offset1:8
	ds_write2st64_b32 v23, v4, v5 offset0:16 offset1:24
	ds_write2st64_b32 v23, v2, v3 offset0:32 offset1:40
	ds_write2st64_b32 v23, v14, v15 offset0:48 offset1:56
	ds_write2st64_b32 v23, v12, v13 offset0:64 offset1:72
	ds_write2st64_b32 v23, v10, v11 offset0:80 offset1:88
	ds_write2st64_b32 v23, v8, v9 offset0:96 offset1:104
	ds_write2st64_b32 v23, v6, v7 offset0:112 offset1:120
	s_waitcnt lgkmcnt(0)
	s_barrier
; __device__ __forceinline__ void conv_tile_v1(Frame& F, const Args& AR, int l, int tile) {
;     ...
;     {
;         float a0[8], a1[8]; float s0 = 0.f, s1 = 0.f;
; #pragma unroll
;         for (int j = 0; j < 8; ++j) { a0[j] = hh[(2 * F.wave) * 512 + F.lane + 64 * j]; a1[j] = hh[(2 * F.wave + 1) * 512 + F.lane + 64 * j]; s0 += a0[j]; s1 += a1[j]; }
;         const float m0 = wave_sum(s0) * (1.0f / 512.0f), m1 = wave_sum(s1) * (1.0f / 512.0f);
;         float q0 = 0.f, q1 = 0.f;
; #pragma unroll
;         for (int j = 0; j < 8; ++j) { const float d0 = a0[j] - m0, d1 = a1[j] - m1; q0 += d0 * d0; q1 += d1 * d1; }
;         q0 = wave_sum(q0); q1 = wave_sum(q1);
;         if (F.lane == 0) { red[4 * F.wave] = m0; red[4 * F.wave + 1] = rsqrtf(q0 * (1.0f / 512.0f) + 1e-5f); red[4 * F.wave + 2] = m1; red[4 * F.wave + 3] = rsqrtf(q1 * (1.0f / 512.0f) + 1e-5f); }
;     }
	ds_read2st64_b32 v[20:21], v31 offset0:8 offset1:9
	ds_read2st64_b32 v[22:23], v31 offset1:1
	ds_read2st64_b32 v[24:25], v31 offset0:10 offset1:11
	ds_read2st64_b32 v[26:27], v31 offset0:12 offset1:13
	ds_read2st64_b32 v[28:29], v31 offset0:14 offset1:15
	ds_read2st64_b32 v[32:33], v31 offset0:2 offset1:3
	ds_read2st64_b32 v[34:35], v31 offset0:4 offset1:5
	ds_read2st64_b32 v[36:37], v31 offset0:6 offset1:7
	s_waitcnt lgkmcnt(7)
	v_mov_b32_e32 v30, v20
	s_waitcnt lgkmcnt(6)
	v_mov_b32_e32 v31, v22
	v_pk_add_f32 v[38:39], v[30:31], 0 op_sel_hi:[1,0]
	v_mov_b32_e32 v22, v21
	v_pk_add_f32 v[20:21], v[38:39], v[22:23]
	s_waitcnt lgkmcnt(5)
	v_mov_b32_e32 v38, v24
	s_waitcnt lgkmcnt(2)
	v_mov_b32_e32 v39, v32
	v_pk_add_f32 v[20:21], v[20:21], v[38:39]
	v_mov_b32_e32 v32, v25
	v_pk_add_f32 v[20:21], v[20:21], v[32:33]
	v_mov_b32_e32 v24, v26
	s_waitcnt lgkmcnt(1)
	v_mov_b32_e32 v25, v34
	v_pk_add_f32 v[20:21], v[20:21], v[24:25]
	v_mov_b32_e32 v34, v27
	v_pk_add_f32 v[20:21], v[20:21], v[34:35]
	v_mov_b32_e32 v26, v28
	s_waitcnt lgkmcnt(0)
	v_mov_b32_e32 v27, v36
	v_pk_add_f32 v[20:21], v[20:21], v[26:27]
	v_mov_b32_e32 v36, v29
	v_pk_add_f32 v[20:21], v[20:21], v[36:37]
	ds_bpermute_b32 v29, v40, v21
	ds_bpermute_b32 v28, v40, v20
	v_cmp_lt_i32_e32 vcc, v198, v218
	s_mov_b32 s0, 0x3b000000
	v_writelane_b32 v250, s16, 58
	v_cndmask_b32_e32 v41, v217, v198, vcc
	v_lshlrev_b32_e32 v41, 2, v41
	s_waitcnt lgkmcnt(0)
	v_pk_add_f32 v[20:21], v[20:21], v[28:29]
	ds_bpermute_b32 v29, v41, v21
	ds_bpermute_b32 v28, v41, v20
	v_cmp_lt_i32_e32 vcc, v229, v218
	v_writelane_b32 v250, s17, 59
	s_waitcnt lgkmcnt(0)
	v_pk_add_f32 v[20:21], v[20:21], v[28:29]
	v_cndmask_b32_e32 v42, v217, v229, vcc
	v_lshlrev_b32_e32 v42, 2, v42
	ds_bpermute_b32 v29, v42, v21
	ds_bpermute_b32 v28, v42, v20
	v_cmp_lt_i32_e32 vcc, v228, v218
	s_waitcnt lgkmcnt(0)
	v_pk_add_f32 v[20:21], v[20:21], v[28:29]
	v_cndmask_b32_e32 v43, v217, v228, vcc
	v_lshlrev_b32_e32 v43, 2, v43
	ds_bpermute_b32 v29, v43, v21
	ds_bpermute_b32 v28, v43, v20
	v_cmp_lt_i32_e32 vcc, v225, v218
	s_waitcnt lgkmcnt(0)
	v_pk_add_f32 v[20:21], v[20:21], v[28:29]
	v_cndmask_b32_e32 v44, v217, v225, vcc
	v_lshlrev_b32_e32 v44, 2, v44
	ds_bpermute_b32 v29, v44, v21
	ds_bpermute_b32 v28, v44, v20
	v_cmp_lt_i32_e32 vcc, v224, v218
	s_waitcnt lgkmcnt(0)
	v_pk_add_f32 v[20:21], v[20:21], v[28:29]
	v_cndmask_b32_e32 v45, v217, v224, vcc
	v_lshlrev_b32_e32 v45, 2, v45
	ds_bpermute_b32 v29, v45, v21
	ds_bpermute_b32 v28, v45, v20
	v_cmp_eq_u32_e32 vcc, 0, v149
	s_waitcnt lgkmcnt(0)
	v_pk_add_f32 v[20:21], v[20:21], v[28:29]
	s_nop 0
	v_pk_fma_f32 v[22:23], v[20:21], s[0:1], v[22:23] op_sel_hi:[1,0,1] neg_lo:[1,0,0] neg_hi:[1,0,0]
	v_pk_fma_f32 v[28:29], v[20:21], s[0:1], v[30:31] op_sel_hi:[1,0,1] neg_lo:[1,0,0] neg_hi:[1,0,0]
	v_pk_mul_f32 v[22:23], v[22:23], v[22:23]
	v_pk_fma_f32 v[24:25], v[20:21], s[0:1], v[24:25] op_sel_hi:[1,0,1] neg_lo:[1,0,0] neg_hi:[1,0,0]
	v_pk_fma_f32 v[22:23], v[28:29], v[28:29], v[22:23]
	v_pk_fma_f32 v[28:29], v[20:21], s[0:1], v[38:39] op_sel_hi:[1,0,1] neg_lo:[1,0,0] neg_hi:[1,0,0]
	v_pk_fma_f32 v[26:27], v[20:21], s[0:1], v[26:27] op_sel_hi:[1,0,1] neg_lo:[1,0,0] neg_hi:[1,0,0]
	v_pk_fma_f32 v[22:23], v[28:29], v[28:29], v[22:23]
	v_pk_fma_f32 v[28:29], v[20:21], s[0:1], v[32:33] op_sel_hi:[1,0,1] neg_lo:[1,0,0] neg_hi:[1,0,0]
	s_nop 0
	v_pk_fma_f32 v[22:23], v[28:29], v[28:29], v[22:23]
	s_nop 0
	v_pk_fma_f32 v[22:23], v[24:25], v[24:25], v[22:23]
	v_pk_fma_f32 v[24:25], v[20:21], s[0:1], v[34:35] op_sel_hi:[1,0,1] neg_lo:[1,0,0] neg_hi:[1,0,0]
	s_nop 0
	v_pk_fma_f32 v[22:23], v[24:25], v[24:25], v[22:23]
	v_pk_fma_f32 v[24:25], v[20:21], s[0:1], v[36:37] op_sel_hi:[1,0,1] neg_lo:[1,0,0] neg_hi:[1,0,0]
	v_pk_fma_f32 v[22:23], v[26:27], v[26:27], v[22:23]
	s_nop 0
	v_pk_fma_f32 v[22:23], v[24:25], v[24:25], v[22:23]
	ds_bpermute_b32 v25, v40, v23
	ds_bpermute_b32 v24, v40, v22
	s_waitcnt lgkmcnt(0)
	v_pk_add_f32 v[22:23], v[22:23], v[24:25]
	ds_bpermute_b32 v25, v41, v23
	ds_bpermute_b32 v24, v41, v22
	s_waitcnt lgkmcnt(0)
	v_pk_add_f32 v[22:23], v[22:23], v[24:25]
	ds_bpermute_b32 v25, v42, v23
	ds_bpermute_b32 v24, v42, v22
	s_waitcnt lgkmcnt(0)
	v_pk_add_f32 v[22:23], v[22:23], v[24:25]
	ds_bpermute_b32 v25, v43, v23
	ds_bpermute_b32 v24, v43, v22
	s_waitcnt lgkmcnt(0)
	v_pk_add_f32 v[22:23], v[22:23], v[24:25]
	ds_bpermute_b32 v25, v44, v23
	ds_bpermute_b32 v24, v44, v22
	s_waitcnt lgkmcnt(0)
	v_pk_add_f32 v[22:23], v[22:23], v[24:25]
	ds_bpermute_b32 v25, v45, v23
	ds_bpermute_b32 v24, v45, v22
	s_and_saveexec_b64 s[4:5], vcc
	s_movk_i32 s24, 0x410
	s_cbranch_execz .LBB0_1368
	s_mov_b32 s8, 0x3b000000
	s_lshl_b32 s0, s12, 4
	v_pk_mul_f32 v[26:27], v[20:21], s[8:9] op_sel_hi:[1,0]
	s_add_i32 s0, s0, 0
	s_waitcnt lgkmcnt(0)
	v_pk_add_f32 v[20:21], v[22:23], v[24:25]
	v_mov_b32_e32 v22, 0x3727c5ac
	s_add_i32 s6, s0, 0x17800
	v_pk_fma_f32 v[20:21], v[20:21], s[8:9], v[22:23] op_sel_hi:[1,0,0]
	s_mov_b32 s0, 0x800000
	v_mul_f32_e32 v22, 0x4b800000, v21
	v_cmp_gt_f32_e32 vcc, s0, v20
	v_cmp_gt_f32_e64 s[0:1], s0, v21
	v_mov_b32_e32 v24, v27
	s_nop 0
	v_cndmask_b32_e64 v21, v21, v22, s[0:1]
	v_rsq_f32_e32 v21, v21
	s_nop 0
	v_mul_f32_e32 v22, 0x45800000, v21
	v_cndmask_b32_e64 v25, v21, v22, s[0:1]
	v_mul_f32_e32 v21, 0x4b800000, v20
	v_cndmask_b32_e32 v20, v20, v21, vcc
	v_rsq_f32_e32 v20, v20
	s_nop 0
	v_mul_f32_e32 v21, 0x45800000, v20
	v_cndmask_b32_e32 v20, v20, v21, vcc
	v_mov_b32_e32 v27, v20
	v_mov_b32_e32 v20, s6
	ds_write_b128 v20, v[24:27]
